# GEMM1+GEMM2 k-loops: running LDS-DMA source pointers (+64 B per k-step, scalar switch to next tile) replace per-k-step cur/next 64-bit adds and per-lane selects (12 VALU -> 4)
# baseline (speedup 1.0000x reference)
.Lgk_i1:
	s_cmp_lg_u32 s10, 29
	s_cbranch_scc1 .Lgp_1
	v_lshl_add_u64 v[198:199], v[194:195], 0, s[2:3]
	v_lshl_add_u64 v[200:201], v[196:197], 0, s[2:3]
.Lgp_1:
	s_addk_i32 s11, 0x8000
	s_cmp_gt_i32 s7, 0
	s_cselect_b32 s0, s11, 0x18000
	s_add_i32 s0, s15, s0
	s_add_i32 s12, s0, 0x4000
	s_mov_b32 m0, s0
	s_add_i32 s11, s0, 0x2000
	global_load_lds_dwordx4 v[198:199], off
	s_mov_b32 m0, s12
	s_add_i32 s1, s0, 0x6000
	v_lshl_add_u64 v[224:225], v[198:199], 0, s[94:95]
	global_load_lds_dwordx4 v[200:201], off
	s_mov_b32 m0, s11
	v_lshl_add_u64 v[222:223], v[200:201], 0, s[94:95]
	global_load_lds_dwordx4 v[224:225], off
	s_mov_b32 m0, s1
	v_lshl_add_u64 v[198:199], v[198:199], 0, 64
	global_load_lds_dwordx4 v[222:223], off
	v_lshl_add_u64 v[200:201], v[200:201], 0, 64
	s_waitcnt vmcnt(8)
	s_branch .LBB0_127

.LBB0_136:
	s_lshl_b32 s10, s52, 15
	v_or_b32_e32 v128, s10, v211
	v_add_u32_e32 v132, v128, v212
	ds_read_b128 v[172:175], v132
	ds_read_b128 v[168:171], v132 offset:1024
	ds_read_b128 v[164:167], v132 offset:2048
	ds_read_b128 v[160:163], v132 offset:3072
	ds_read_b128 v[156:159], v132 offset:4096
	ds_read_b128 v[152:155], v132 offset:5120
	ds_read_b128 v[136:139], v132 offset:6144
	ds_read_b128 v[128:131], v132 offset:7168
	v_add_u32_e32 v132, s41, v132
	ds_read_b128 v[144:147], v132 offset:16384
	ds_read_b128 v[148:151], v132 offset:17408
	ds_read_b128 v[140:143], v132 offset:18432
	ds_read_b128 v[132:135], v132 offset:19456
	s_cmp_lt_u32 s7, 29
	s_cselect_b64 s[0:1], -1, 0
	s_nor_b64 s[12:13], s[8:9], s[0:1]
	s_cbranch_scc1 .LBB0_138
	s_cmp_lg_u32 s7, 29
	s_cbranch_scc1 .Lgp_2
	v_lshl_add_u64 v[188:189], v[192:193], 0, s[2:3]
	v_lshl_add_u64 v[186:187], v[190:191], 0, s[2:3]
.Lgp_2:
	s_addk_i32 s10, 0x8000
	s_cmp_gt_i32 s52, 0
	s_cselect_b32 s0, s10, 0x18000
	s_add_i32 s0, s15, s0
	s_add_i32 s11, s0, 0x4000
	s_mov_b32 m0, s0
	s_add_i32 s10, s0, 0x2000
	global_load_lds_dwordx4 v[188:189], off
	s_mov_b32 m0, s11
	s_add_i32 s1, s0, 0x6000
	v_lshl_add_u64 v[200:201], v[188:189], 0, s[94:95]
	global_load_lds_dwordx4 v[186:187], off
	s_mov_b32 m0, s10
	v_lshl_add_u64 v[198:199], v[186:187], 0, s[94:95]
	global_load_lds_dwordx4 v[200:201], off
	s_mov_b32 m0, s1
	v_lshl_add_u64 v[188:189], v[188:189], 0, 64
	global_load_lds_dwordx4 v[198:199], off
	v_lshl_add_u64 v[186:187], v[186:187], 0, 64

.Lgk_i3:
	s_cmp_lg_u32 s39, 29
	s_cbranch_scc1 .Lgp_3
	v_lshl_add_u64 v[190:191], v[186:187], 0, s[8:9]
	v_lshl_add_u64 v[192:193], v[188:189], 0, s[8:9]
.Lgp_3:
	s_addk_i32 s54, 0x8000
	s_cmp_gt_i32 s64, 0
	s_cselect_b32 s2, s54, 0x18000
	s_add_i32 s2, s35, s2
	s_add_i32 s13, s2, 0x4000
	s_mov_b32 m0, s2
	s_add_i32 s12, s2, 0x2000
	global_load_lds_dwordx4 v[190:191], off
	s_mov_b32 m0, s13
	s_add_i32 s3, s2, 0x6000
	v_lshl_add_u64 v[200:201], v[190:191], 0, s[72:73]
	global_load_lds_dwordx4 v[192:193], off
	s_mov_b32 m0, s12
	v_lshl_add_u64 v[198:199], v[192:193], 0, s[72:73]
	global_load_lds_dwordx4 v[200:201], off
	s_mov_b32 m0, s3
	v_lshl_add_u64 v[190:191], v[190:191], 0, 64
	global_load_lds_dwordx4 v[198:199], off
	v_lshl_add_u64 v[192:193], v[192:193], 0, 64
	s_waitcnt vmcnt(8)
	s_branch .LBB0_701

.LBB0_710:
	s_lshl_b32 s54, s64, 15
	v_or_b32_e32 v128, s54, v202
	v_add_u32_e32 v132, v128, v203
	ds_read_b128 v[172:175], v132
	ds_read_b128 v[168:171], v132 offset:1024
	ds_read_b128 v[164:167], v132 offset:2048
	ds_read_b128 v[160:163], v132 offset:3072
	ds_read_b128 v[156:159], v132 offset:4096
	ds_read_b128 v[152:155], v132 offset:5120
	ds_read_b128 v[136:139], v132 offset:6144
	ds_read_b128 v[128:131], v132 offset:7168
	v_add_u32_e32 v132, s36, v132
	ds_read_b128 v[144:147], v132 offset:16384
	ds_read_b128 v[148:151], v132 offset:17408
	ds_read_b128 v[140:143], v132 offset:18432
	ds_read_b128 v[132:135], v132 offset:19456
	s_cmp_lt_u32 s39, 29
	s_cselect_b64 s[2:3], -1, 0
	s_nor_b64 s[12:13], s[16:17], s[2:3]
	s_cbranch_scc1 .LBB0_712
	s_cmp_lg_u32 s39, 29
	s_cbranch_scc1 .Lgp_4
	v_lshl_add_u64 v[190:191], v[186:187], 0, s[8:9]
	v_lshl_add_u64 v[192:193], v[188:189], 0, s[8:9]
.Lgp_4:
	s_addk_i32 s54, 0x8000
	s_cmp_gt_i32 s64, 0
	s_cselect_b32 s2, s54, 0x18000
	s_add_i32 s2, s35, s2
	s_add_i32 s55, s2, 0x4000
	s_mov_b32 m0, s2
	s_add_i32 s54, s2, 0x2000
	global_load_lds_dwordx4 v[190:191], off
	s_mov_b32 m0, s55
	s_add_i32 s3, s2, 0x6000
	v_lshl_add_u64 v[200:201], v[190:191], 0, s[72:73]
	global_load_lds_dwordx4 v[192:193], off
	s_mov_b32 m0, s54
	v_lshl_add_u64 v[198:199], v[192:193], 0, s[72:73]
	global_load_lds_dwordx4 v[200:201], off
	s_mov_b32 m0, s3
	v_lshl_add_u64 v[190:191], v[190:191], 0, 64
	global_load_lds_dwordx4 v[198:199], off
	v_lshl_add_u64 v[192:193], v[192:193], 0, 64

.Lgk_i4:
	s_cmp_lg_u32 s12, 29
	s_cbranch_scc1 .Lgp_5
	v_lshl_add_u64 v[198:199], v[194:195], 0, s[2:3]
	v_lshl_add_u64 v[200:201], v[196:197], 0, s[2:3]
.Lgp_5:
	s_addk_i32 s13, 0x8000
	s_cmp_gt_i32 s64, 0
	s_cselect_b32 s0, s13, 0x18000
	s_add_i32 s0, s35, s0
	s_add_i32 s9, s0, 0x4000
	s_mov_b32 m0, s0
	s_add_i32 s8, s0, 0x2000
	global_load_lds_dwordx4 v[198:199], off
	s_mov_b32 m0, s9
	s_add_i32 s1, s0, 0x6000
	v_lshl_add_u64 v[216:217], v[198:199], 0, s[72:73]
	global_load_lds_dwordx4 v[200:201], off
	s_mov_b32 m0, s8
	v_lshl_add_u64 v[214:215], v[200:201], 0, s[72:73]
	global_load_lds_dwordx4 v[216:217], off
	s_mov_b32 m0, s1
	v_lshl_add_u64 v[198:199], v[198:199], 0, 64
	global_load_lds_dwordx4 v[214:215], off
	v_lshl_add_u64 v[200:201], v[200:201], 0, 64
	s_waitcnt vmcnt(8)
	s_branch .LBB0_720

.LBB0_729:
	s_lshl_b32 s13, s38, 15
	v_or_b32_e32 v128, s13, v202
	v_add_u32_e32 v132, v128, v203
	ds_read_b128 v[172:175], v132
	ds_read_b128 v[168:171], v132 offset:1024
	ds_read_b128 v[164:167], v132 offset:2048
	ds_read_b128 v[160:163], v132 offset:3072
	ds_read_b128 v[156:159], v132 offset:4096
	ds_read_b128 v[152:155], v132 offset:5120
	ds_read_b128 v[136:139], v132 offset:6144
	ds_read_b128 v[128:131], v132 offset:7168
	v_add_u32_e32 v132, s36, v132
	ds_read_b128 v[144:147], v132 offset:16384
	ds_read_b128 v[148:151], v132 offset:17408
	ds_read_b128 v[140:143], v132 offset:18432
	ds_read_b128 v[132:135], v132 offset:19456
	s_cmp_lt_u32 s12, 29
	s_cselect_b64 s[0:1], -1, 0
	s_nor_b64 s[8:9], s[16:17], s[0:1]
	s_cbranch_scc1 .LBB0_731
	s_cmp_lg_u32 s12, 29
	s_cbranch_scc1 .Lgp_6
	v_lshl_add_u64 v[188:189], v[192:193], 0, s[2:3]
	v_lshl_add_u64 v[186:187], v[190:191], 0, s[2:3]
.Lgp_6:
	s_addk_i32 s13, 0x8000
	s_cmp_gt_i32 s38, 0
	s_cselect_b32 s0, s13, 0x18000
	s_add_i32 s0, s35, s0
	s_add_i32 s39, s0, 0x4000
	s_mov_b32 m0, s0
	s_add_i32 s13, s0, 0x2000
	global_load_lds_dwordx4 v[188:189], off
	s_mov_b32 m0, s39
	s_add_i32 s1, s0, 0x6000
	v_lshl_add_u64 v[200:201], v[188:189], 0, s[72:73]
	global_load_lds_dwordx4 v[186:187], off
	s_mov_b32 m0, s13
	v_lshl_add_u64 v[198:199], v[186:187], 0, s[72:73]
	global_load_lds_dwordx4 v[200:201], off
	s_mov_b32 m0, s1
	v_lshl_add_u64 v[188:189], v[188:189], 0, 64
	global_load_lds_dwordx4 v[198:199], off
	v_lshl_add_u64 v[186:187], v[186:187], 0, 64
